# streaming (nt) loads for the once-read f32 sources in the prologue, on top of the P7 epilogue staging-load hoist and dead spill-reload removal
# baseline (speedup 1.0000x reference)
; #define LAS __attribute__((address_space(3)))
; DI unsigned cvtpk(float lo, float hi) { f32x2_t v = {lo, hi}; bf16x2_t b = __builtin_convertvector(v, bf16x2_t); return __builtin_bit_cast(unsigned, b); }
;     if (pitch == 0) pitch = K;
;     const int nblk = N / 32, kb = item / nblk, nb = item % nblk, k0 = 64 * kb, n0 = 32 * nb;
;     f32x4 wv[8];
; #pragma unroll
;     for (int i = 0; i < 8; ++i) wv[i] = *(const f32x4*)(W + (size_t)(k0 + 8 * i + (lane >> 3)) * N + n0 + 4 * (lane & 7));
;     if (kscale) {
; #pragma unroll
;         for (int i = 0; i < 8; ++i) wv[i] = wv[i] * kscale[k0 + 8 * i + (lane >> 3)]; }
; #pragma unroll
;     for (int i = 0; i < 8; ++i) { LAS float* d = scr + (8 * i + (lane >> 3)) * 33 + 4 * (lane & 7); d[0] = wv[i][0]; d[1] = wv[i][1]; d[2] = wv[i][2]; d[3] = wv[i][3]; }
;     asm volatile("s_waitcnt lgkmcnt(0)" ::: "memory");
;     const int c = lane & 7;
; #pragma unroll
;     for (int j = 0; j < 4; ++j) { const int n = (lane >> 3) + 8 * j; const LAS float* s = scr + (8 * c) * 33 + n;
;         u32x4 o; o.x = cvtpk(s[0 * 33], s[1 * 33]); o.y = cvtpk(s[2 * 33], s[3 * 33]); o.z = cvtpk(s[4 * 33], s[5 * 33]); o.w = cvtpk(s[6 * 33], s[7 * 33]);
;         *(u32x4*)(WT + (size_t)dest_row(mode, n0 + n) * pitch + k0 + 8 * c) = o; }
;     asm volatile("s_waitcnt lgkmcnt(0)" ::: "memory");
.LBB0_8:
	s_cmpk_gt_i32 s22, 0x31ff
	s_mov_b64 s[26:27], -1
	s_cbranch_scc0 .LBB0_28
	s_cmpk_gt_u32 s22, 0x3dff
	s_cbranch_scc0 .LBB0_25
	s_cmpk_gt_u32 s22, 0x45ff
	s_cbranch_scc0 .LBB0_22
	s_cmpk_gt_u32 s22, 0x4dff
	s_cbranch_scc0 .LBB0_19
	s_cmpk_gt_u32 s22, 0x79ff
	s_cbranch_scc0 .LBB0_14
	s_add_i32 s23, s22, 0x8600
	s_and_b32 s23, s23, 0xffc0
	s_and_b32 s28, s3, 0x7e0
	v_add_u32_e32 v2, s23, v1
	s_lshl_b32 s24, s28, 2
	v_ashrrev_i32_e32 v3, 31, v2
	v_lshl_add_u64 v[4:5], v[38:39], 0, s[24:25]
	v_lshlrev_b64 v[2:3], 13, v[2:3]
	v_lshl_add_u64 v[30:31], v[4:5], 0, v[2:3]
	v_add_co_u32_e32 v6, vcc, 0x10000, v30
	s_lshl_b32 s24, s23, 1
	s_nop 0
	v_addc_co_u32_e32 v7, vcc, 0, v31, vcc
	v_add_co_u32_e32 v10, vcc, 0x20000, v30
	global_load_dwordx4 v[2:5], v[30:31], off nt
	s_nop 0
	global_load_dwordx4 v[6:9], v[6:7], off nt
	v_addc_co_u32_e32 v11, vcc, 0, v31, vcc
	v_add_co_u32_e32 v14, vcc, 0x30000, v30
	v_add_u32_e32 v59, s28, v1
	s_nop 0
	v_addc_co_u32_e32 v15, vcc, 0, v31, vcc
	v_add_co_u32_e32 v18, vcc, 0x40000, v30
	global_load_dwordx4 v[10:13], v[10:11], off nt
	s_nop 0
	global_load_dwordx4 v[14:17], v[14:15], off nt
	v_addc_co_u32_e32 v19, vcc, 0, v31, vcc
	v_add_co_u32_e32 v22, vcc, 0x50000, v30
	v_lshl_add_u64 v[60:61], v[48:49], 0, s[24:25]
	s_nop 0
	v_addc_co_u32_e32 v23, vcc, 0, v31, vcc
	global_load_dwordx4 v[18:21], v[18:19], off nt
	s_nop 0
	global_load_dwordx4 v[22:25], v[22:23], off nt
	v_add_co_u32_e32 v26, vcc, 0x60000, v30
	v_add_u32_e32 v86, s28, v35
	s_nop 0
	v_addc_co_u32_e32 v27, vcc, 0, v31, vcc
	global_load_dwordx4 v[26:29], v[26:27], off nt
	v_add_co_u32_e32 v30, vcc, 0x70000, v30
	v_mad_i64_i32 v[84:85], s[26:27], v59, s17, v[60:61]
	s_nop 0
	v_addc_co_u32_e32 v31, vcc, 0, v31, vcc
	global_load_dwordx4 v[30:33], v[30:31], off nt
	v_mad_i64_i32 v[86:87], s[26:27], v86, s17, v[60:61]
	s_waitcnt vmcnt(7)
	ds_write2_b32 v67, v2, v3 offset1:1
	ds_write2_b32 v67, v4, v5 offset0:2 offset1:3
	s_waitcnt vmcnt(6)
	ds_write2_b32 v68, v6, v7 offset1:1
	ds_write2_b32 v69, v8, v9 offset1:1
	s_waitcnt vmcnt(5)
	ds_write2_b32 v70, v10, v11 offset1:1
	ds_write2_b32 v71, v12, v13 offset1:1
	s_waitcnt vmcnt(4)
	ds_write2_b32 v72, v14, v15 offset1:1
	ds_write2_b32 v73, v16, v17 offset1:1
	s_waitcnt vmcnt(3)
	ds_write2_b32 v74, v18, v19 offset1:1
	ds_write2_b32 v75, v20, v21 offset1:1
	s_waitcnt vmcnt(2)
	ds_write2_b32 v76, v22, v23 offset1:1
	ds_write2_b32 v77, v24, v25 offset1:1
	s_waitcnt vmcnt(1)
	ds_write2_b32 v78, v26, v27 offset1:1
	ds_write2_b32 v79, v28, v29 offset1:1
	s_waitcnt vmcnt(0)
	ds_write2_b32 v80, v30, v31 offset1:1
	ds_write2_b32 v81, v32, v33 offset1:1
	s_waitcnt lgkmcnt(0)
	ds_read2_b32 v[6:7], v65 offset0:33 offset1:41
	ds_read2_b32 v[8:9], v65 offset1:8
	ds_read2_b32 v[10:11], v65 offset0:66 offset1:74
	ds_read2_b32 v[12:13], v65 offset0:99 offset1:107
	ds_read2_b32 v[14:15], v65 offset0:132 offset1:140
	ds_read2_b32 v[16:17], v65 offset0:165 offset1:173
	ds_read2_b32 v[18:19], v65 offset0:198 offset1:206
	ds_read2_b32 v[20:21], v65 offset0:231 offset1:239
	ds_read2_b32 v[22:23], v65 offset0:49 offset1:57
	ds_read2_b32 v[24:25], v65 offset0:16 offset1:24
	ds_read2_b32 v[26:27], v65 offset0:82 offset1:90
	ds_read2_b32 v[28:29], v65 offset0:115 offset1:123
	ds_read2_b32 v[30:31], v65 offset0:148 offset1:156
	ds_read2_b32 v[32:33], v65 offset0:181 offset1:189
	ds_read2_b32 v[88:89], v65 offset0:214 offset1:222
	ds_read2_b32 v[90:91], v65 offset0:247 offset1:255
	s_waitcnt lgkmcnt(14)
	v_cvt_pk_bf16_f32 v2, v8, v6
	s_waitcnt lgkmcnt(12)
	v_cvt_pk_bf16_f32 v3, v10, v12
	s_waitcnt lgkmcnt(10)
	v_cvt_pk_bf16_f32 v4, v14, v16
	s_waitcnt lgkmcnt(8)
	v_cvt_pk_bf16_f32 v5, v18, v20
	v_cvt_pk_bf16_f32 v6, v9, v7
	v_cvt_pk_bf16_f32 v7, v11, v13
	v_cvt_pk_bf16_f32 v8, v15, v17
	v_cvt_pk_bf16_f32 v9, v19, v21
	global_store_dwordx4 v[84:85], v[2:5], off
	global_store_dwordx4 v[86:87], v[6:9], off
	s_waitcnt lgkmcnt(6)
	v_cvt_pk_bf16_f32 v2, v24, v22
	v_add_u32_e32 v6, s28, v63
	s_waitcnt lgkmcnt(4)
	v_cvt_pk_bf16_f32 v3, v26, v28
	s_waitcnt lgkmcnt(2)
	v_cvt_pk_bf16_f32 v4, v30, v32
	s_waitcnt lgkmcnt(0)
	v_cvt_pk_bf16_f32 v5, v88, v90
	v_mad_i64_i32 v[6:7], s[26:27], v6, s17, v[60:61]
	global_store_dwordx4 v[6:7], v[2:5], off
	v_add_u32_e32 v6, s28, v64
	v_mad_i64_i32 v[6:7], s[26:27], v6, s17, v[60:61]
	v_cvt_pk_bf16_f32 v2, v25, v23
	v_cvt_pk_bf16_f32 v3, v27, v29
	v_cvt_pk_bf16_f32 v4, v31, v33
	v_cvt_pk_bf16_f32 v5, v89, v91
	global_store_dwordx4 v[6:7], v[2:5], off
	s_waitcnt lgkmcnt(0)
	s_mov_b64 s[26:27], 0
;     if (pitch == 0) pitch = K;
;     const int nblk = N / 32, kb = item / nblk, nb = item % nblk, k0 = 64 * kb, n0 = 32 * nb;
;     f32x4 wv[8];
; #pragma unroll
;     for (int i = 0; i < 8; ++i) wv[i] = *(const f32x4*)(W + (size_t)(k0 + 8 * i + (lane >> 3)) * N + n0 + 4 * (lane & 7));
;     if (kscale) {
; #pragma unroll
;         for (int i = 0; i < 8; ++i) wv[i] = wv[i] * kscale[k0 + 8 * i + (lane >> 3)]; }
.LBB0_14:
	s_andn2_b64 vcc, exec, s[26:27]
	s_cbranch_vccnz .LBB0_18
	s_add_i32 s23, s22, 0xb200
	s_and_b32 s24, s23, 0xffff
	s_mul_i32 s24, s24, 0xba2f
	s_lshr_b32 s24, s24, 24
	s_mul_i32 s26, s24, 0x160
	s_sub_i32 s26, s23, s26
	s_lshl_b32 s23, s24, 6
	s_lshl_b32 s24, s26, 7
	v_add_u32_e32 v60, s23, v1
	s_and_b32 s24, s24, 0x3ff80
	v_lshl_add_u64 v[26:27], v[40:41], 0, s[24:25]
	v_add_u32_e32 v4, 8, v60
	v_add_u32_e32 v10, 16, v60
	v_add_u32_e32 v12, 24, v60
	v_add_u32_e32 v18, 32, v60
	v_add_u32_e32 v20, 40, v60
	v_add_u32_e32 v28, 48, v60
	v_add_u32_e32 v30, 56, v60
	v_mad_i64_i32 v[2:3], s[28:29], v60, s18, v[26:27]
	v_mad_i64_i32 v[4:5], s[28:29], v4, s18, v[26:27]
	v_mad_i64_i32 v[10:11], s[28:29], v10, s18, v[26:27]
	v_mad_i64_i32 v[12:13], s[28:29], v12, s18, v[26:27]
	v_mad_i64_i32 v[18:19], s[28:29], v18, s18, v[26:27]
	v_mad_i64_i32 v[20:21], s[28:29], v20, s18, v[26:27]
	v_mad_i64_i32 v[28:29], s[28:29], v28, s18, v[26:27]
	v_mad_i64_i32 v[26:27], s[28:29], v30, s18, v[26:27]
	global_load_dwordx4 v[6:9], v[2:3], off nt
	s_nop 0
	global_load_dwordx4 v[2:5], v[4:5], off nt
	s_nop 0
	global_load_dwordx4 v[14:17], v[10:11], off nt
	s_nop 0
	global_load_dwordx4 v[10:13], v[12:13], off nt
	s_nop 0
	global_load_dwordx4 v[22:25], v[18:19], off nt
	s_nop 0
	global_load_dwordx4 v[18:21], v[20:21], off nt
	s_nop 0
	global_load_dwordx4 v[30:33], v[28:29], off nt
	s_nop 0
	global_load_dwordx4 v[26:29], v[26:27], off nt
	s_andn2_b64 vcc, exec, s[0:1]
	s_cbranch_vccnz .LBB0_17
	v_ashrrev_i32_e32 v61, 31, v60
	v_lshl_add_u64 v[60:61], v[60:61], 2, s[46:47]
	global_load_dword v84, v[60:61], off nt
	global_load_dword v86, v[60:61], off offset:32 nt
	global_load_dword v88, v[60:61], off offset:64 nt
	global_load_dword v90, v[60:61], off offset:96 nt
	global_load_dword v92, v[60:61], off offset:128 nt
	global_load_dword v94, v[60:61], off offset:160 nt
	global_load_dword v96, v[60:61], off offset:192 nt
	s_nop 0
	global_load_dword v60, v[60:61], off offset:224 nt
	s_waitcnt vmcnt(7)
	v_pk_mul_f32 v[8:9], v[8:9], v[84:85] op_sel_hi:[1,0]
	v_pk_mul_f32 v[6:7], v[6:7], v[84:85] op_sel_hi:[1,0]
	s_waitcnt vmcnt(6)
	v_pk_mul_f32 v[4:5], v[4:5], v[86:87] op_sel_hi:[1,0]
	v_pk_mul_f32 v[2:3], v[2:3], v[86:87] op_sel_hi:[1,0]
	s_waitcnt vmcnt(5)
	v_pk_mul_f32 v[16:17], v[16:17], v[88:89] op_sel_hi:[1,0]
	v_pk_mul_f32 v[14:15], v[14:15], v[88:89] op_sel_hi:[1,0]
	s_waitcnt vmcnt(4)
	v_pk_mul_f32 v[12:13], v[12:13], v[90:91] op_sel_hi:[1,0]
	v_pk_mul_f32 v[10:11], v[10:11], v[90:91] op_sel_hi:[1,0]
	s_waitcnt vmcnt(3)
	v_pk_mul_f32 v[24:25], v[24:25], v[92:93] op_sel_hi:[1,0]
	v_pk_mul_f32 v[22:23], v[22:23], v[92:93] op_sel_hi:[1,0]
	s_waitcnt vmcnt(2)
	v_pk_mul_f32 v[20:21], v[20:21], v[94:95] op_sel_hi:[1,0]
	v_pk_mul_f32 v[18:19], v[18:19], v[94:95] op_sel_hi:[1,0]
	s_waitcnt vmcnt(1)
	v_pk_mul_f32 v[32:33], v[32:33], v[96:97] op_sel_hi:[1,0]
	v_pk_mul_f32 v[30:31], v[30:31], v[96:97] op_sel_hi:[1,0]
	s_waitcnt vmcnt(0)
	v_pk_mul_f32 v[28:29], v[28:29], v[60:61] op_sel_hi:[1,0]
	v_pk_mul_f32 v[26:27], v[26:27], v[60:61] op_sel_hi:[1,0]

; #define LAS __attribute__((address_space(3)))
; DI unsigned cvtpk(float lo, float hi) { f32x2_t v = {lo, hi}; bf16x2_t b = __builtin_convertvector(v, bf16x2_t); return __builtin_bit_cast(unsigned, b); }
;     if (pitch == 0) pitch = K;
;     const int nblk = N / 32, kb = item / nblk, nb = item % nblk, k0 = 64 * kb, n0 = 32 * nb;
;     f32x4 wv[8];
; #pragma unroll
;     for (int i = 0; i < 8; ++i) wv[i] = *(const f32x4*)(W + (size_t)(k0 + 8 * i + (lane >> 3)) * N + n0 + 4 * (lane & 7));
;     if (kscale) {
; #pragma unroll
;         for (int i = 0; i < 8; ++i) wv[i] = wv[i] * kscale[k0 + 8 * i + (lane >> 3)]; }
; #pragma unroll
;     for (int i = 0; i < 8; ++i) { LAS float* d = scr + (8 * i + (lane >> 3)) * 33 + 4 * (lane & 7); d[0] = wv[i][0]; d[1] = wv[i][1]; d[2] = wv[i][2]; d[3] = wv[i][3]; }
;     asm volatile("s_waitcnt lgkmcnt(0)" ::: "memory");
;     const int c = lane & 7;
; #pragma unroll
;     for (int j = 0; j < 4; ++j) { const int n = (lane >> 3) + 8 * j; const LAS float* s = scr + (8 * c) * 33 + n;
;         u32x4 o; o.x = cvtpk(s[0 * 33], s[1 * 33]); o.y = cvtpk(s[2 * 33], s[3 * 33]); o.z = cvtpk(s[4 * 33], s[5 * 33]); o.w = cvtpk(s[6 * 33], s[7 * 33]);
;         *(u32x4*)(WT + (size_t)dest_row(mode, n0 + n) * pitch + k0 + 8 * c) = o; }
;     asm volatile("s_waitcnt lgkmcnt(0)" ::: "memory");
.LBB0_19:
	s_andn2_b64 vcc, exec, s[26:27]
	s_cbranch_vccnz .LBB0_21
	s_add_i32 s23, s22, 0xba00
	s_and_b32 s23, s23, 0xffc0
	s_and_b32 s26, s3, 0x7e0
	v_add_u32_e32 v2, s23, v1
	s_lshl_b32 s24, s26, 2
	v_ashrrev_i32_e32 v3, 31, v2
	v_lshl_add_u64 v[4:5], v[42:43], 0, s[24:25]
	v_lshlrev_b64 v[2:3], 13, v[2:3]
	v_lshl_add_u64 v[30:31], v[4:5], 0, v[2:3]
	v_add_co_u32_e32 v6, vcc, 0x10000, v30
	v_add_u32_e32 v84, s26, v35
	s_nop 0
	v_addc_co_u32_e32 v7, vcc, 0, v31, vcc
	v_add_co_u32_e32 v10, vcc, 0x20000, v30
	global_load_dwordx4 v[2:5], v[30:31], off nt
	s_nop 0
	global_load_dwordx4 v[6:9], v[6:7], off nt
	v_addc_co_u32_e32 v11, vcc, 0, v31, vcc
	v_add_co_u32_e32 v14, vcc, 0x30000, v30
	s_lshl_b32 s24, s23, 1
	s_nop 0
	v_addc_co_u32_e32 v15, vcc, 0, v31, vcc
	v_add_co_u32_e32 v18, vcc, 0x40000, v30
	global_load_dwordx4 v[10:13], v[10:11], off nt
	s_nop 0
	global_load_dwordx4 v[14:17], v[14:15], off nt
	v_addc_co_u32_e32 v19, vcc, 0, v31, vcc
	v_add_co_u32_e32 v22, vcc, 0x50000, v30
	v_ashrrev_i32_e32 v85, 31, v84
	s_nop 0
	v_addc_co_u32_e32 v23, vcc, 0, v31, vcc
	global_load_dwordx4 v[18:21], v[18:19], off nt
	s_nop 0
	global_load_dwordx4 v[22:25], v[22:23], off nt
	v_add_co_u32_e32 v26, vcc, 0x60000, v30
	v_lshl_add_u64 v[86:87], v[52:53], 0, s[24:25]
	s_nop 0
	v_addc_co_u32_e32 v27, vcc, 0, v31, vcc
	global_load_dwordx4 v[26:29], v[26:27], off nt
	v_add_co_u32_e32 v30, vcc, 0x70000, v30
	v_lshlrev_b64 v[84:85], 12, v[84:85]
	s_nop 0
	v_addc_co_u32_e32 v31, vcc, 0, v31, vcc
	global_load_dwordx4 v[30:33], v[30:31], off nt
	v_add_u32_e32 v60, s26, v1
	v_lshl_add_u64 v[84:85], v[86:87], 0, v[84:85]
	v_ashrrev_i32_e32 v61, 31, v60
	v_lshlrev_b64 v[60:61], 12, v[60:61]
	v_lshl_add_u64 v[60:61], v[86:87], 0, v[60:61]
	s_waitcnt vmcnt(7)
	ds_write2_b32 v67, v2, v3 offset1:1
	ds_write2_b32 v67, v4, v5 offset0:2 offset1:3
	s_waitcnt vmcnt(6)
	ds_write2_b32 v68, v6, v7 offset1:1
	ds_write2_b32 v69, v8, v9 offset1:1
	s_waitcnt vmcnt(5)
	ds_write2_b32 v70, v10, v11 offset1:1
	ds_write2_b32 v71, v12, v13 offset1:1
	s_waitcnt vmcnt(4)
	ds_write2_b32 v72, v14, v15 offset1:1
	ds_write2_b32 v73, v16, v17 offset1:1
	s_waitcnt vmcnt(3)
	ds_write2_b32 v74, v18, v19 offset1:1
	ds_write2_b32 v75, v20, v21 offset1:1
	s_waitcnt vmcnt(2)
	ds_write2_b32 v76, v22, v23 offset1:1
	ds_write2_b32 v77, v24, v25 offset1:1
	s_waitcnt vmcnt(1)
	ds_write2_b32 v78, v26, v27 offset1:1
	ds_write2_b32 v79, v28, v29 offset1:1
	s_waitcnt vmcnt(0)
	ds_write2_b32 v80, v30, v31 offset1:1
	ds_write2_b32 v81, v32, v33 offset1:1
	s_waitcnt lgkmcnt(0)
	ds_read2_b32 v[6:7], v65 offset0:33 offset1:41
	ds_read2_b32 v[8:9], v65 offset1:8
	ds_read2_b32 v[10:11], v65 offset0:66 offset1:74
	ds_read2_b32 v[12:13], v65 offset0:99 offset1:107
	ds_read2_b32 v[14:15], v65 offset0:132 offset1:140
	ds_read2_b32 v[16:17], v65 offset0:165 offset1:173
	ds_read2_b32 v[18:19], v65 offset0:198 offset1:206
	ds_read2_b32 v[20:21], v65 offset0:231 offset1:239
	ds_read2_b32 v[22:23], v65 offset0:49 offset1:57
	ds_read2_b32 v[24:25], v65 offset0:16 offset1:24
	ds_read2_b32 v[26:27], v65 offset0:82 offset1:90
	ds_read2_b32 v[28:29], v65 offset0:115 offset1:123
	ds_read2_b32 v[30:31], v65 offset0:148 offset1:156
	ds_read2_b32 v[32:33], v65 offset0:181 offset1:189
	ds_read2_b32 v[88:89], v65 offset0:214 offset1:222
	s_waitcnt lgkmcnt(13)
	v_cvt_pk_bf16_f32 v2, v8, v6
	s_waitcnt lgkmcnt(11)
	v_cvt_pk_bf16_f32 v3, v10, v12
	v_cvt_pk_bf16_f32 v6, v9, v7
	v_cvt_pk_bf16_f32 v7, v11, v13
	ds_read2_b32 v[10:11], v65 offset0:247 offset1:255
	s_waitcnt lgkmcnt(10)
	v_cvt_pk_bf16_f32 v8, v15, v17
	s_waitcnt lgkmcnt(8)
	v_cvt_pk_bf16_f32 v9, v19, v21
	global_store_dwordx4 v[84:85], v[6:9], off
	v_cvt_pk_bf16_f32 v4, v14, v16
	v_cvt_pk_bf16_f32 v5, v18, v20
	v_add_u32_e32 v6, s26, v63
	v_ashrrev_i32_e32 v7, 31, v6
	v_lshlrev_b64 v[6:7], 12, v[6:7]
	global_store_dwordx4 v[60:61], v[2:5], off
	v_lshl_add_u64 v[6:7], v[86:87], 0, v[6:7]
	s_waitcnt lgkmcnt(6)
	v_cvt_pk_bf16_f32 v2, v24, v22
	s_waitcnt lgkmcnt(4)
	v_cvt_pk_bf16_f32 v3, v26, v28
	s_waitcnt lgkmcnt(2)
	v_cvt_pk_bf16_f32 v4, v30, v32
	s_waitcnt lgkmcnt(0)
	v_cvt_pk_bf16_f32 v5, v88, v10
	global_store_dwordx4 v[6:7], v[2:5], off
	v_add_u32_e32 v6, s26, v64
	v_ashrrev_i32_e32 v7, 31, v6
	v_lshlrev_b64 v[6:7], 12, v[6:7]
	v_cvt_pk_bf16_f32 v2, v25, v23
	v_cvt_pk_bf16_f32 v3, v27, v29
	v_cvt_pk_bf16_f32 v4, v31, v33
	v_cvt_pk_bf16_f32 v5, v89, v11
	v_lshl_add_u64 v[6:7], v[86:87], 0, v[6:7]
	global_store_dwordx4 v[6:7], v[2:5], off
	s_waitcnt lgkmcnt(0)

; #define LAS __attribute__((address_space(3)))
; DI unsigned cvtpk(float lo, float hi) { f32x2_t v = {lo, hi}; bf16x2_t b = __builtin_convertvector(v, bf16x2_t); return __builtin_bit_cast(unsigned, b); }
;     if (pitch == 0) pitch = K;
;     const int nblk = N / 32, kb = item / nblk, nb = item % nblk, k0 = 64 * kb, n0 = 32 * nb;
;     f32x4 wv[8];
; #pragma unroll
;     for (int i = 0; i < 8; ++i) wv[i] = *(const f32x4*)(W + (size_t)(k0 + 8 * i + (lane >> 3)) * N + n0 + 4 * (lane & 7));
;     if (kscale) {
; #pragma unroll
;         for (int i = 0; i < 8; ++i) wv[i] = wv[i] * kscale[k0 + 8 * i + (lane >> 3)]; }
; #pragma unroll
;     for (int i = 0; i < 8; ++i) { LAS float* d = scr + (8 * i + (lane >> 3)) * 33 + 4 * (lane & 7); d[0] = wv[i][0]; d[1] = wv[i][1]; d[2] = wv[i][2]; d[3] = wv[i][3]; }
;     asm volatile("s_waitcnt lgkmcnt(0)" ::: "memory");
;     const int c = lane & 7;
; #pragma unroll
;     for (int j = 0; j < 4; ++j) { const int n = (lane >> 3) + 8 * j; const LAS float* s = scr + (8 * c) * 33 + n;
;         u32x4 o; o.x = cvtpk(s[0 * 33], s[1 * 33]); o.y = cvtpk(s[2 * 33], s[3 * 33]); o.z = cvtpk(s[4 * 33], s[5 * 33]); o.w = cvtpk(s[6 * 33], s[7 * 33]);
;         *(u32x4*)(WT + (size_t)dest_row(mode, n0 + n) * pitch + k0 + 8 * c) = o; }
;     asm volatile("s_waitcnt lgkmcnt(0)" ::: "memory");
.LBB0_22:
	s_andn2_b64 vcc, exec, s[26:27]
	s_cbranch_vccnz .LBB0_24
	s_add_i32 s23, s22, 0xc200
	s_and_b32 s23, s23, 0xffc0
	s_and_b32 s26, s3, 0x7e0
	v_add_u32_e32 v2, s23, v1
	s_lshl_b32 s24, s26, 2
	v_ashrrev_i32_e32 v3, 31, v2
	v_lshl_add_u64 v[4:5], v[44:45], 0, s[24:25]
	v_lshlrev_b64 v[2:3], 13, v[2:3]
	v_lshl_add_u64 v[30:31], v[4:5], 0, v[2:3]
	v_add_co_u32_e32 v6, vcc, 0x10000, v30
	v_add_u32_e32 v84, s26, v35
	s_nop 0
	v_addc_co_u32_e32 v7, vcc, 0, v31, vcc
	v_add_co_u32_e32 v10, vcc, 0x20000, v30
	global_load_dwordx4 v[2:5], v[30:31], off nt
	s_nop 0
	global_load_dwordx4 v[6:9], v[6:7], off nt
	v_addc_co_u32_e32 v11, vcc, 0, v31, vcc
	v_add_co_u32_e32 v14, vcc, 0x30000, v30
	s_lshl_b32 s24, s23, 1
	s_nop 0
	v_addc_co_u32_e32 v15, vcc, 0, v31, vcc
	v_add_co_u32_e32 v18, vcc, 0x40000, v30
	global_load_dwordx4 v[10:13], v[10:11], off nt
	s_nop 0
	global_load_dwordx4 v[14:17], v[14:15], off nt
	v_addc_co_u32_e32 v19, vcc, 0, v31, vcc
	v_add_co_u32_e32 v22, vcc, 0x50000, v30
	v_ashrrev_i32_e32 v85, 31, v84
	s_nop 0
	v_addc_co_u32_e32 v23, vcc, 0, v31, vcc
	global_load_dwordx4 v[18:21], v[18:19], off nt
	s_nop 0
	global_load_dwordx4 v[22:25], v[22:23], off nt
	v_add_co_u32_e32 v26, vcc, 0x60000, v30
	v_lshl_add_u64 v[86:87], v[54:55], 0, s[24:25]
	s_nop 0
	v_addc_co_u32_e32 v27, vcc, 0, v31, vcc
	global_load_dwordx4 v[26:29], v[26:27], off nt
	v_add_co_u32_e32 v30, vcc, 0x70000, v30
	v_lshlrev_b64 v[84:85], 12, v[84:85]
	s_nop 0
	v_addc_co_u32_e32 v31, vcc, 0, v31, vcc
	global_load_dwordx4 v[30:33], v[30:31], off nt
	v_add_u32_e32 v60, s26, v1
	v_lshl_add_u64 v[84:85], v[86:87], 0, v[84:85]
	v_ashrrev_i32_e32 v61, 31, v60
	v_lshlrev_b64 v[60:61], 12, v[60:61]
	v_lshl_add_u64 v[60:61], v[86:87], 0, v[60:61]
	s_waitcnt vmcnt(7)
	ds_write2_b32 v67, v2, v3 offset1:1
	ds_write2_b32 v67, v4, v5 offset0:2 offset1:3
	s_waitcnt vmcnt(6)
	ds_write2_b32 v68, v6, v7 offset1:1
	ds_write2_b32 v69, v8, v9 offset1:1
	s_waitcnt vmcnt(5)
	ds_write2_b32 v70, v10, v11 offset1:1
	ds_write2_b32 v71, v12, v13 offset1:1
	s_waitcnt vmcnt(4)
	ds_write2_b32 v72, v14, v15 offset1:1
	ds_write2_b32 v73, v16, v17 offset1:1
	s_waitcnt vmcnt(3)
	ds_write2_b32 v74, v18, v19 offset1:1
	ds_write2_b32 v75, v20, v21 offset1:1
	s_waitcnt vmcnt(2)
	ds_write2_b32 v76, v22, v23 offset1:1
	ds_write2_b32 v77, v24, v25 offset1:1
	s_waitcnt vmcnt(1)
	ds_write2_b32 v78, v26, v27 offset1:1
	ds_write2_b32 v79, v28, v29 offset1:1
	s_waitcnt vmcnt(0)
	ds_write2_b32 v80, v30, v31 offset1:1
	ds_write2_b32 v81, v32, v33 offset1:1
	s_waitcnt lgkmcnt(0)
	ds_read2_b32 v[6:7], v65 offset0:33 offset1:41
	ds_read2_b32 v[8:9], v65 offset1:8
	ds_read2_b32 v[10:11], v65 offset0:66 offset1:74
	ds_read2_b32 v[12:13], v65 offset0:99 offset1:107
	ds_read2_b32 v[14:15], v65 offset0:132 offset1:140
	ds_read2_b32 v[16:17], v65 offset0:165 offset1:173
	ds_read2_b32 v[18:19], v65 offset0:198 offset1:206
	ds_read2_b32 v[20:21], v65 offset0:231 offset1:239
	ds_read2_b32 v[22:23], v65 offset0:49 offset1:57
	ds_read2_b32 v[24:25], v65 offset0:16 offset1:24
	ds_read2_b32 v[26:27], v65 offset0:82 offset1:90
	ds_read2_b32 v[28:29], v65 offset0:115 offset1:123
	ds_read2_b32 v[30:31], v65 offset0:148 offset1:156
	ds_read2_b32 v[32:33], v65 offset0:181 offset1:189
	ds_read2_b32 v[88:89], v65 offset0:214 offset1:222
	s_waitcnt lgkmcnt(13)
	v_cvt_pk_bf16_f32 v2, v8, v6
	s_waitcnt lgkmcnt(11)
	v_cvt_pk_bf16_f32 v3, v10, v12
	v_cvt_pk_bf16_f32 v6, v9, v7
	v_cvt_pk_bf16_f32 v7, v11, v13
	ds_read2_b32 v[10:11], v65 offset0:247 offset1:255
	s_waitcnt lgkmcnt(10)
	v_cvt_pk_bf16_f32 v8, v15, v17
	s_waitcnt lgkmcnt(8)
	v_cvt_pk_bf16_f32 v9, v19, v21
	global_store_dwordx4 v[84:85], v[6:9], off
	v_cvt_pk_bf16_f32 v4, v14, v16
	v_cvt_pk_bf16_f32 v5, v18, v20
	v_add_u32_e32 v6, s26, v63
	v_ashrrev_i32_e32 v7, 31, v6
	v_lshlrev_b64 v[6:7], 12, v[6:7]
	global_store_dwordx4 v[60:61], v[2:5], off
	v_lshl_add_u64 v[6:7], v[86:87], 0, v[6:7]
	s_waitcnt lgkmcnt(6)
	v_cvt_pk_bf16_f32 v2, v24, v22
	s_waitcnt lgkmcnt(4)
	v_cvt_pk_bf16_f32 v3, v26, v28
	s_waitcnt lgkmcnt(2)
	v_cvt_pk_bf16_f32 v4, v30, v32
	s_waitcnt lgkmcnt(0)
	v_cvt_pk_bf16_f32 v5, v88, v10
	global_store_dwordx4 v[6:7], v[2:5], off
	v_add_u32_e32 v6, s26, v64
	v_ashrrev_i32_e32 v7, 31, v6
	v_lshlrev_b64 v[6:7], 12, v[6:7]
	v_cvt_pk_bf16_f32 v2, v25, v23
	v_cvt_pk_bf16_f32 v3, v27, v29
	v_cvt_pk_bf16_f32 v4, v31, v33
	v_cvt_pk_bf16_f32 v5, v89, v11
	v_lshl_add_u64 v[6:7], v[86:87], 0, v[6:7]
	global_store_dwordx4 v[6:7], v[2:5], off
	s_waitcnt lgkmcnt(0)

; #define LAS __attribute__((address_space(3)))
; DI unsigned cvtpk(float lo, float hi) { f32x2_t v = {lo, hi}; bf16x2_t b = __builtin_convertvector(v, bf16x2_t); return __builtin_bit_cast(unsigned, b); }
;     if (pitch == 0) pitch = K;
;     const int nblk = N / 32, kb = item / nblk, nb = item % nblk, k0 = 64 * kb, n0 = 32 * nb;
;     f32x4 wv[8];
; #pragma unroll
;     for (int i = 0; i < 8; ++i) wv[i] = *(const f32x4*)(W + (size_t)(k0 + 8 * i + (lane >> 3)) * N + n0 + 4 * (lane & 7));
;     if (kscale) {
; #pragma unroll
;         for (int i = 0; i < 8; ++i) wv[i] = wv[i] * kscale[k0 + 8 * i + (lane >> 3)]; }
; #pragma unroll
;     for (int i = 0; i < 8; ++i) { LAS float* d = scr + (8 * i + (lane >> 3)) * 33 + 4 * (lane & 7); d[0] = wv[i][0]; d[1] = wv[i][1]; d[2] = wv[i][2]; d[3] = wv[i][3]; }
;     asm volatile("s_waitcnt lgkmcnt(0)" ::: "memory");
;     const int c = lane & 7;
; #pragma unroll
;     for (int j = 0; j < 4; ++j) { const int n = (lane >> 3) + 8 * j; const LAS float* s = scr + (8 * c) * 33 + n;
;         u32x4 o; o.x = cvtpk(s[0 * 33], s[1 * 33]); o.y = cvtpk(s[2 * 33], s[3 * 33]); o.z = cvtpk(s[4 * 33], s[5 * 33]); o.w = cvtpk(s[6 * 33], s[7 * 33]);
;         *(u32x4*)(WT + (size_t)dest_row(mode, n0 + n) * pitch + k0 + 8 * c) = o; }
;     asm volatile("s_waitcnt lgkmcnt(0)" ::: "memory");
.LBB0_25:
	s_andn2_b64 vcc, exec, s[26:27]
	s_cbranch_vccnz .LBB0_27
	s_add_i32 s23, s22, 0xffffce00
	s_lshr_b32 s24, s23, 10
	s_lshl_b64 s[26:27], s[24:25], 23
	v_readlane_b32 s90, v250, 28
	v_readlane_b32 s91, v250, 29
	s_add_u32 s28, s90, s26
	s_addc_u32 s29, s91, s27
	s_lshl_b64 s[26:27], s[24:25], 22
	v_readlane_b32 s24, v250, 34
	s_add_u32 s24, s24, s26
	v_readlane_b32 s26, v250, 35
	s_addc_u32 s30, s26, s27
	s_and_b32 s31, s3, 0x7e0
	s_and_b32 s23, s23, 0x3c0
	s_lshl_b32 s26, s31, 2
	v_add_u32_e32 v2, s23, v1
	s_add_u32 s26, s28, s26
	s_addc_u32 s27, s29, 0
	v_ashrrev_i32_e32 v3, 31, v2
	v_lshl_add_u64 v[4:5], s[26:27], 0, v[36:37]
	v_lshlrev_b64 v[2:3], 13, v[2:3]
	v_lshl_add_u64 v[30:31], v[4:5], 0, v[2:3]
	v_add_co_u32_e32 v6, vcc, s10, v30
	s_lshl_b32 s23, s23, 1
	s_nop 0
	v_addc_co_u32_e32 v7, vcc, 0, v31, vcc
	v_add_co_u32_e32 v10, vcc, s11, v30
	global_load_dwordx4 v[2:5], v[30:31], off nt
	s_nop 0
	global_load_dwordx4 v[6:9], v[6:7], off nt
	v_addc_co_u32_e32 v11, vcc, 0, v31, vcc
	v_add_co_u32_e32 v14, vcc, s12, v30
	v_add_u32_e32 v60, s31, v1
	s_nop 0
	v_addc_co_u32_e32 v15, vcc, 0, v31, vcc
	v_add_co_u32_e32 v18, vcc, s13, v30
	global_load_dwordx4 v[10:13], v[10:11], off nt
	s_nop 0
	global_load_dwordx4 v[14:17], v[14:15], off nt
	v_addc_co_u32_e32 v19, vcc, 0, v31, vcc
	v_add_co_u32_e32 v22, vcc, s14, v30
	s_add_u32 s26, s24, s23
	s_nop 0
	v_addc_co_u32_e32 v23, vcc, 0, v31, vcc
	global_load_dwordx4 v[18:21], v[18:19], off nt
	s_nop 0
	global_load_dwordx4 v[22:25], v[22:23], off nt
	v_add_co_u32_e32 v26, vcc, s15, v30
	v_mov_b32_e32 v59, v37
	s_nop 0
	v_addc_co_u32_e32 v27, vcc, 0, v31, vcc
	global_load_dwordx4 v[26:29], v[26:27], off nt
	v_add_co_u32_e32 v30, vcc, s16, v30
	v_ashrrev_i32_e32 v61, 31, v60
	s_nop 0
	v_addc_co_u32_e32 v31, vcc, 0, v31, vcc
	global_load_dwordx4 v[30:33], v[30:31], off nt
	s_addc_u32 s27, s30, 0
	v_lshlrev_b64 v[60:61], 11, v[60:61]
	v_lshl_add_u64 v[86:87], s[26:27], 0, v[58:59]
	v_add_u32_e32 v84, s31, v35
	v_lshl_add_u64 v[60:61], v[86:87], 0, v[60:61]
	v_ashrrev_i32_e32 v85, 31, v84
	v_lshlrev_b64 v[84:85], 11, v[84:85]
	v_lshl_add_u64 v[84:85], v[86:87], 0, v[84:85]
	s_waitcnt vmcnt(7)
	ds_write2_b32 v67, v2, v3 offset1:1
	ds_write2_b32 v67, v4, v5 offset0:2 offset1:3
	s_waitcnt vmcnt(6)
	ds_write2_b32 v68, v6, v7 offset1:1
	ds_write2_b32 v69, v8, v9 offset1:1
	s_waitcnt vmcnt(5)
	ds_write2_b32 v70, v10, v11 offset1:1
	ds_write2_b32 v71, v12, v13 offset1:1
	s_waitcnt vmcnt(4)
	ds_write2_b32 v72, v14, v15 offset1:1
	ds_write2_b32 v73, v16, v17 offset1:1
	s_waitcnt vmcnt(3)
	ds_write2_b32 v74, v18, v19 offset1:1
	ds_write2_b32 v75, v20, v21 offset1:1
	s_waitcnt vmcnt(2)
	ds_write2_b32 v76, v22, v23 offset1:1
	ds_write2_b32 v77, v24, v25 offset1:1
	s_waitcnt vmcnt(1)
	ds_write2_b32 v78, v26, v27 offset1:1
	ds_write2_b32 v79, v28, v29 offset1:1
	s_waitcnt vmcnt(0)
	ds_write2_b32 v80, v30, v31 offset1:1
	ds_write2_b32 v81, v32, v33 offset1:1
	s_waitcnt lgkmcnt(0)
	ds_read2_b32 v[6:7], v65 offset0:33 offset1:41
	ds_read2_b32 v[8:9], v65 offset1:8
	ds_read2_b32 v[10:11], v65 offset0:66 offset1:74
	ds_read2_b32 v[12:13], v65 offset0:99 offset1:107
	ds_read2_b32 v[14:15], v65 offset0:132 offset1:140
	ds_read2_b32 v[16:17], v65 offset0:165 offset1:173
	ds_read2_b32 v[18:19], v65 offset0:198 offset1:206
	ds_read2_b32 v[20:21], v65 offset0:231 offset1:239
	ds_read2_b32 v[22:23], v65 offset0:49 offset1:57
	s_waitcnt lgkmcnt(7)
	v_cvt_pk_bf16_f32 v2, v8, v6
	s_waitcnt lgkmcnt(5)
	v_cvt_pk_bf16_f32 v3, v10, v12
	s_waitcnt lgkmcnt(3)
	v_cvt_pk_bf16_f32 v4, v14, v16
	s_waitcnt lgkmcnt(1)
	v_cvt_pk_bf16_f32 v5, v18, v20
	global_store_dwordx4 v[60:61], v[2:5], off
	v_cvt_pk_bf16_f32 v6, v9, v7
	v_cvt_pk_bf16_f32 v7, v11, v13
	v_cvt_pk_bf16_f32 v8, v15, v17
	v_cvt_pk_bf16_f32 v9, v19, v21
	ds_read2_b32 v[10:11], v65 offset0:16 offset1:24
	ds_read2_b32 v[12:13], v65 offset0:82 offset1:90
	ds_read2_b32 v[14:15], v65 offset0:115 offset1:123
	ds_read2_b32 v[16:17], v65 offset0:148 offset1:156
	ds_read2_b32 v[18:19], v65 offset0:181 offset1:189
	ds_read2_b32 v[20:21], v65 offset0:214 offset1:222
	ds_read2_b32 v[24:25], v65 offset0:247 offset1:255
	global_store_dwordx4 v[84:85], v[6:9], off
	s_waitcnt lgkmcnt(6)
	v_cvt_pk_bf16_f32 v2, v10, v22
	s_waitcnt lgkmcnt(4)
	v_cvt_pk_bf16_f32 v3, v12, v14
	v_add_u32_e32 v6, s31, v63
	v_ashrrev_i32_e32 v7, 31, v6
	v_lshlrev_b64 v[6:7], 11, v[6:7]
	s_waitcnt lgkmcnt(2)
	v_cvt_pk_bf16_f32 v4, v16, v18
	s_waitcnt lgkmcnt(0)
	v_cvt_pk_bf16_f32 v5, v20, v24
	v_lshl_add_u64 v[6:7], v[86:87], 0, v[6:7]
	global_store_dwordx4 v[6:7], v[2:5], off
	v_add_u32_e32 v6, s31, v64
	v_ashrrev_i32_e32 v7, 31, v6
	v_lshlrev_b64 v[6:7], 11, v[6:7]
	v_cvt_pk_bf16_f32 v2, v11, v23
	v_cvt_pk_bf16_f32 v3, v13, v15
	v_cvt_pk_bf16_f32 v4, v17, v19
	v_cvt_pk_bf16_f32 v5, v21, v25
	v_lshl_add_u64 v[6:7], v[86:87], 0, v[6:7]
	global_store_dwordx4 v[6:7], v[2:5], off
	s_waitcnt lgkmcnt(0)

; #define LAS __attribute__((address_space(3)))
; DI unsigned cvtpk(float lo, float hi) { f32x2_t v = {lo, hi}; bf16x2_t b = __builtin_convertvector(v, bf16x2_t); return __builtin_bit_cast(unsigned, b); }
; DI int dest_row(int mode, int n) {
;     if (mode == 1) { if (n >= 1536 && n < 3584) { const int hd = (n - 1536) >> 7, d = (n - 1536) & 127, half = d >> 6, i = d & 63; return 1536 + hd * 128 + 8 * (i >> 2) + 4 * half + (i & 3); } return n; }
;     if (mode == 2) { const int gv = n >= FF ? 1 : 0, f = n - gv * FF; return 256 * (f >> 7) + 128 * gv + (f & 127); }
;     return n;
; }
;     if (pitch == 0) pitch = K;
;     const int nblk = N / 32, kb = item / nblk, nb = item % nblk, k0 = 64 * kb, n0 = 32 * nb;
;     f32x4 wv[8];
; #pragma unroll
;     for (int i = 0; i < 8; ++i) wv[i] = *(const f32x4*)(W + (size_t)(k0 + 8 * i + (lane >> 3)) * N + n0 + 4 * (lane & 7));
;     if (kscale) {
; #pragma unroll
;         for (int i = 0; i < 8; ++i) wv[i] = wv[i] * kscale[k0 + 8 * i + (lane >> 3)]; }
; #pragma unroll
;     for (int i = 0; i < 8; ++i) { LAS float* d = scr + (8 * i + (lane >> 3)) * 33 + 4 * (lane & 7); d[0] = wv[i][0]; d[1] = wv[i][1]; d[2] = wv[i][2]; d[3] = wv[i][3]; }
;     asm volatile("s_waitcnt lgkmcnt(0)" ::: "memory");
;     const int c = lane & 7;
; #pragma unroll
;     for (int j = 0; j < 4; ++j) { const int n = (lane >> 3) + 8 * j; const LAS float* s = scr + (8 * c) * 33 + n;
;         u32x4 o; o.x = cvtpk(s[0 * 33], s[1 * 33]); o.y = cvtpk(s[2 * 33], s[3 * 33]); o.z = cvtpk(s[4 * 33], s[5 * 33]); o.w = cvtpk(s[6 * 33], s[7 * 33]);
;         *(u32x4*)(WT + (size_t)dest_row(mode, n0 + n) * pitch + k0 + 8 * c) = o; }
;     asm volatile("s_waitcnt lgkmcnt(0)" ::: "memory");
.LBB0_28:
	s_andn2_b64 vcc, exec, s[26:27]
	s_cbranch_vccnz .LBB0_7
	s_mul_hi_i32 s23, s22, 0x51eb851f
	s_lshr_b32 s24, s23, 31
	s_ashr_i32 s23, s23, 7
	s_add_i32 s23, s23, s24
	s_mul_i32 s24, s23, 0xffffce00
	s_lshl_b32 s26, s23, 6
	s_add_i32 s28, s3, s24
	v_add_u32_e32 v32, s26, v1
	s_ashr_i32 s29, s28, 31
	v_lshl_add_u64 v[30:31], s[28:29], 2, v[46:47]
	v_add_u32_e32 v4, 8, v32
	v_add_u32_e32 v10, 16, v32
	v_add_u32_e32 v12, 24, v32
	v_add_u32_e32 v18, 32, v32
	v_add_u32_e32 v20, 40, v32
	v_mad_i64_i32 v[2:3], s[30:31], v32, s20, v[30:31]
	v_mad_i64_i32 v[6:7], s[30:31], v4, s20, v[30:31]
	v_mad_i64_i32 v[10:11], s[30:31], v10, s20, v[30:31]
	v_mad_i64_i32 v[14:15], s[30:31], v12, s20, v[30:31]
	v_mad_i64_i32 v[18:19], s[30:31], v18, s20, v[30:31]
	v_mad_i64_i32 v[22:23], s[30:31], v20, s20, v[30:31]
	global_load_dwordx4 v[2:5], v[2:3], off nt
	s_nop 0
	global_load_dwordx4 v[6:9], v[6:7], off nt
	s_nop 0
	global_load_dwordx4 v[10:13], v[10:11], off nt
	s_nop 0
	global_load_dwordx4 v[14:17], v[14:15], off nt
	s_nop 0
	global_load_dwordx4 v[18:21], v[18:19], off nt
	s_nop 0
	global_load_dwordx4 v[22:25], v[22:23], off nt
	v_add_u32_e32 v26, 48, v32
	v_mad_i64_i32 v[26:27], s[30:31], v26, s20, v[30:31]
	global_load_dwordx4 v[26:29], v[26:27], off nt
	v_add_u32_e32 v32, 56, v32
	v_mad_i64_i32 v[30:31], s[30:31], v32, s20, v[30:31]
	global_load_dwordx4 v[30:33], v[30:31], off nt
	s_mulk_i32 s23, 0x9c00
	v_add_u32_e32 v59, s23, v66
	v_add_u32_e32 v86, s28, v1
	v_add_u32_e32 v85, 16, v59
	v_lshrrev_b32_e32 v88, 4, v86
	v_and_b32_e32 v84, 0x78, v59
	v_add_u32_e32 v87, 0xfffffa00, v86
	v_and_b32_e32 v89, 0xf83, v86
	v_and_b32_e32 v92, 0x78, v85
	v_and_b32_e32 v85, 4, v88
	v_or3_b32 v84, v84, v89, v85
	v_cmp_gt_u32_e32 vcc, s21, v87
	s_ashr_i32 s27, s26, 31
	v_lshl_add_u64 v[60:61], s[26:27], 1, v[56:57]
	v_cndmask_b32_e32 v84, v86, v84, vcc
	v_ashrrev_i32_e32 v85, 31, v84
	v_add_u32_e32 v90, 8, v86
	v_lshlrev_b64 v[84:85], 12, v[84:85]
	v_lshrrev_b32_e32 v88, 4, v90
	v_add_u32_e32 v91, 0xfffffa08, v86
	v_and_b32_e32 v88, 4, v88
	v_cmp_gt_u32_e32 vcc, s21, v91
	s_waitcnt vmcnt(7)
	ds_write2_b32 v67, v2, v3 offset1:1
	ds_write2_b32 v67, v4, v5 offset0:2 offset1:3
	s_waitcnt vmcnt(6)
	ds_write2_b32 v68, v6, v7 offset1:1
	ds_write2_b32 v69, v8, v9 offset1:1
	s_waitcnt vmcnt(5)
	ds_write2_b32 v70, v10, v11 offset1:1
	ds_write2_b32 v71, v12, v13 offset1:1
	s_waitcnt vmcnt(4)
	ds_write2_b32 v72, v14, v15 offset1:1
	ds_write2_b32 v73, v16, v17 offset1:1
	s_waitcnt vmcnt(3)
	ds_write2_b32 v74, v18, v19 offset1:1
	ds_write2_b32 v75, v20, v21 offset1:1
	s_waitcnt vmcnt(2)
	ds_write2_b32 v76, v22, v23 offset1:1
	ds_write2_b32 v77, v24, v25 offset1:1
	s_waitcnt vmcnt(1)
	ds_write2_b32 v78, v26, v27 offset1:1
	ds_write2_b32 v79, v28, v29 offset1:1
	s_waitcnt vmcnt(0)
	ds_write2_b32 v80, v30, v31 offset1:1
	ds_write2_b32 v81, v32, v33 offset1:1
	s_waitcnt lgkmcnt(0)
	ds_read2_b32 v[6:7], v65 offset0:33 offset1:41
	ds_read2_b32 v[8:9], v65 offset1:8
	ds_read2_b32 v[10:11], v65 offset0:66 offset1:74
	ds_read2_b32 v[12:13], v65 offset0:99 offset1:107
	ds_read2_b32 v[14:15], v65 offset0:132 offset1:140
	ds_read2_b32 v[16:17], v65 offset0:165 offset1:173
	ds_read2_b32 v[18:19], v65 offset0:198 offset1:206
	ds_read2_b32 v[20:21], v65 offset0:231 offset1:239
	v_lshl_add_u64 v[22:23], v[60:61], 0, v[84:85]
	s_waitcnt lgkmcnt(6)
	v_cvt_pk_bf16_f32 v2, v8, v6
	s_waitcnt lgkmcnt(4)
	v_cvt_pk_bf16_f32 v3, v10, v12
	s_waitcnt lgkmcnt(2)
	v_cvt_pk_bf16_f32 v4, v14, v16
	s_waitcnt lgkmcnt(0)
	v_cvt_pk_bf16_f32 v5, v18, v20
	global_store_dwordx4 v[22:23], v[2:5], off
	v_cvt_pk_bf16_f32 v6, v9, v7
	v_cvt_pk_bf16_f32 v7, v11, v13
	v_and_b32_e32 v2, 0xf83, v90
	v_or3_b32 v2, v92, v2, v88
	v_cndmask_b32_e32 v2, v90, v2, vcc
	v_ashrrev_i32_e32 v3, 31, v2
	v_lshlrev_b64 v[2:3], 12, v[2:3]
	v_cvt_pk_bf16_f32 v8, v15, v17
	v_cvt_pk_bf16_f32 v9, v19, v21
	v_lshl_add_u64 v[2:3], v[60:61], 0, v[2:3]
	ds_read2_b32 v[10:11], v65 offset0:16 offset1:24
	ds_read2_b32 v[12:13], v65 offset0:49 offset1:57
	ds_read2_b32 v[14:15], v65 offset0:82 offset1:90
	ds_read2_b32 v[16:17], v65 offset0:115 offset1:123
	ds_read2_b32 v[18:19], v65 offset0:148 offset1:156
	ds_read2_b32 v[20:21], v65 offset0:181 offset1:189
	ds_read2_b32 v[22:23], v65 offset0:214 offset1:222
	ds_read2_b32 v[24:25], v65 offset0:247 offset1:255
	global_store_dwordx4 v[2:3], v[6:9], off
	s_waitcnt lgkmcnt(6)
	v_cvt_pk_bf16_f32 v2, v10, v12
	s_waitcnt lgkmcnt(4)
	v_cvt_pk_bf16_f32 v3, v14, v16
	v_add_u32_e32 v6, 16, v86
	v_add_u32_e32 v8, 32, v59
	v_lshrrev_b32_e32 v9, 4, v6
	v_add_u32_e32 v7, 0xfffffa10, v86
	v_and_b32_e32 v8, 0x78, v8
	v_and_b32_e32 v9, 4, v9
	v_and_b32_e32 v10, 0xf83, v6
	v_or3_b32 v8, v8, v10, v9
	v_cmp_gt_u32_e32 vcc, s21, v7
	s_waitcnt lgkmcnt(2)
	v_cvt_pk_bf16_f32 v4, v18, v20
	s_waitcnt lgkmcnt(0)
	v_cvt_pk_bf16_f32 v5, v22, v24
	v_cndmask_b32_e32 v6, v6, v8, vcc
	v_ashrrev_i32_e32 v7, 31, v6
	v_lshlrev_b64 v[6:7], 12, v[6:7]
	v_lshl_add_u64 v[6:7], v[60:61], 0, v[6:7]
	global_store_dwordx4 v[6:7], v[2:5], off
	s_nop 1
	v_add_u32_e32 v2, 24, v86
	v_add_u32_e32 v4, 48, v59
	v_lshrrev_b32_e32 v5, 4, v2
	v_add_u32_e32 v3, 0xfffffa18, v86
	v_and_b32_e32 v4, 0x78, v4
	v_and_b32_e32 v5, 4, v5
	v_and_b32_e32 v6, 0xf83, v2
	v_or3_b32 v4, v4, v6, v5
	v_cmp_gt_u32_e32 vcc, s21, v3
	v_cvt_pk_bf16_f32 v3, v15, v17
	v_cvt_pk_bf16_f32 v5, v23, v25
	v_cndmask_b32_e32 v6, v2, v4, vcc
	v_ashrrev_i32_e32 v7, 31, v6
	v_lshlrev_b64 v[6:7], 12, v[6:7]
	v_cvt_pk_bf16_f32 v2, v11, v13
	v_cvt_pk_bf16_f32 v4, v19, v21
	v_lshl_add_u64 v[6:7], v[60:61], 0, v[6:7]
	global_store_dwordx4 v[6:7], v[2:5], off
	s_waitcnt lgkmcnt(0)
	s_branch .LBB0_7
; DI float wave_sum(float v) {
; #pragma unroll
;     for (int o = 1; o < 64; o <<= 1) v += __shfl_xor(v, o);
;     return v;
; DI void p0_prologue(const Ctx& C, LAS unsigned char* lds, int wave, bool first) {
;     ...
;         f32x4 gmix[8];
; #pragma unroll
;         for (int j = 0; j < 8; ++j) gmix[j] = *((const f32x4*)C.g_mix + lane + 64 * j);
;         for (int m = gw; m < MT; m += NGW) rms_row_to_bf16_g(m < MP ? C.xp + (size_t)m * DM : C.xs + (size_t)(m - MP) * DM, gmix, U + (size_t)m * DM, lane);
.LBB0_30:
	s_cmp_lt_i32 s60, 0x8200
	s_cselect_b64 s[8:9], -1, 0
	s_ashr_i32 s61, s60, 31
	s_lshl_b64 s[0:1], s[60:61], 13
	v_writelane_b32 v250, s0, 45
	s_mov_b64 s[16:17], s[56:57]
	s_mov_b64 s[18:19], s[58:59]
	v_writelane_b32 v250, s1, 46
	v_writelane_b32 v250, s8, 47
	s_mov_b64 s[10:11], s[50:51]
	s_mov_b64 s[12:13], s[52:53]
	v_writelane_b32 v250, s9, 48
	s_and_b64 vcc, exec, s[8:9]
	v_writelane_b32 v250, s4, 49
	v_ashrrev_i32_e32 v35, 31, v34
	v_mbcnt_lo_u32_b32 v206, -1, 0
	v_writelane_b32 v250, s5, 50
	v_writelane_b32 v250, s6, 51
	v_writelane_b32 v250, s7, 52
	v_writelane_b32 v250, s8, 53
	v_writelane_b32 v250, s9, 54
	v_writelane_b32 v250, s10, 55
	v_writelane_b32 v250, s11, 56
	v_writelane_b32 v250, s12, 57
	v_writelane_b32 v250, s13, 58
	v_writelane_b32 v250, s14, 59
	v_writelane_b32 v250, s15, 60
	v_writelane_b32 v250, s16, 61
	v_writelane_b32 v250, s17, 62
	v_writelane_b32 v250, s18, 63
	v_writelane_b32 v249, s19, 0
	s_cbranch_vccz .LBB0_35
	v_readlane_b32 s10, v250, 20
	v_readlane_b32 s11, v250, 21
	v_mbcnt_hi_u32_b32 v36, -1, v206
	v_mov_b32_e32 v2, s10
	v_mov_b32_e32 v3, s11
	v_lshl_add_u64 v[30:31], v[34:35], 4, v[2:3]
	v_add_co_u32_e32 v14, vcc, 0x1000, v30
	v_and_b32_e32 v1, 64, v36
	s_nop 0
	v_addc_co_u32_e32 v15, vcc, 0, v31, vcc
	global_load_dwordx4 v[2:5], v[14:15], off offset:3072 nt
	global_load_dwordx4 v[6:9], v[14:15], off offset:2048 nt
	global_load_dwordx4 v[10:13], v[14:15], off offset:1024 nt
	s_nop 0
	global_load_dwordx4 v[14:17], v[14:15], off nt
	s_nop 0
	global_load_dwordx4 v[18:21], v[30:31], off offset:3072 nt
	global_load_dwordx4 v[22:25], v[30:31], off offset:2048 nt
	global_load_dwordx4 v[26:29], v[30:31], off offset:1024 nt
	s_nop 0
	global_load_dwordx4 v[30:33], v[30:31], off nt
	v_add_u32_e32 v37, 64, v1
	v_xor_b32_e32 v1, 1, v36
	v_cmp_lt_i32_e32 vcc, v1, v37
	v_xor_b32_e32 v38, 2, v36
	v_xor_b32_e32 v39, 4, v36
	v_cndmask_b32_e32 v1, v36, v1, vcc
	v_cmp_lt_i32_e32 vcc, v38, v37
	v_xor_b32_e32 v40, 8, v36
	v_readlane_b32 s12, v250, 22
	v_cndmask_b32_e32 v38, v36, v38, vcc
	v_cmp_lt_i32_e32 vcc, v39, v37
	v_readlane_b32 s13, v250, 23
	v_readlane_b32 s14, v250, 24
	v_readlane_b32 s15, v250, 25
	v_readlane_b32 s16, v250, 26
	v_readlane_b32 s17, v250, 27
	v_readlane_b32 s18, v250, 28
	v_readlane_b32 s19, v250, 29
	v_readlane_b32 s20, v250, 30
	v_readlane_b32 s21, v250, 31
	v_readlane_b32 s22, v250, 32
	v_readlane_b32 s23, v250, 33
	v_cndmask_b32_e32 v39, v36, v39, vcc
	v_cmp_lt_i32_e32 vcc, v40, v37
	v_xor_b32_e32 v41, 16, v36
	v_readlane_b32 s9, v250, 19
	v_cndmask_b32_e32 v40, v36, v40, vcc
	v_cmp_lt_i32_e32 vcc, v41, v37
	v_xor_b32_e32 v42, 32, v36
	v_readlane_b32 s12, v250, 2
	v_cndmask_b32_e32 v41, v36, v41, vcc
	v_cmp_lt_i32_e32 vcc, v42, v37
	s_ashr_i32 s39, s38, 31
	v_readlane_b32 s8, v250, 45
	v_cndmask_b32_e32 v36, v36, v42, vcc
	v_readlane_b32 s9, v250, 46
	v_readlane_b32 s13, v250, 3
	s_add_u32 s24, s12, s8
	s_movk_i32 s3, 0x1000
	s_mov_b32 s1, 0
	v_lshlrev_b32_e32 v1, 2, v1
	v_lshlrev_b32_e32 v38, 2, v38
	v_lshlrev_b32_e32 v39, 2, v39
	v_lshlrev_b32_e32 v40, 2, v40
	v_lshlrev_b32_e32 v41, 2, v41
	v_lshlrev_b32_e32 v42, 2, v36
	v_lshl_add_u64 v[36:37], v[34:35], 3, s[58:59]
	s_addc_u32 s25, s13, s9
	s_lshl_b64 s[26:27], s[38:39], 13
	v_mov_b32_e32 v43, 0x358637bd
	s_mov_b32 s8, 0x800000
	s_mov_b64 s[28:29], s[60:61]
	s_branch .LBB0_33
; DI unsigned cvtpk(float lo, float hi) { f32x2_t v = {lo, hi}; bf16x2_t b = __builtin_convertvector(v, bf16x2_t); return __builtin_bit_cast(unsigned, b); }
; DI void rms_row_to_bf16_g(const float* xrow, const f32x4 (&gg)[8], bf16_t* orow, int lane) {
;     f32x4 v[8]; float s = 0.f;
; #pragma unroll
;     for (int j = 0; j < 8; ++j) { v[j] = *((const f32x4*)xrow + lane + 64 * j); s += (v[j][0] * v[j][0] + v[j][1] * v[j][1]) + (v[j][2] * v[j][2] + v[j][3] * v[j][3]); }
;     const float rstd = rsqrtf(wave_sum(s) * (1.0f / DM) + EPS);
; #pragma unroll
;     for (int j = 0; j < 8; ++j) { u32x2 w; w.x = cvtpk(v[j][0] * rstd * gg[j][0], v[j][1] * rstd * gg[j][1]); w.y = cvtpk(v[j][2] * rstd * gg[j][2], v[j][3] * rstd * gg[j][3]);
;         *((u32x2*)orow + lane + 64 * j) = w; }
; }
; DI void p0_prologue(const Ctx& C, LAS unsigned char* lds, int wave, bool first) {
;     ...
;         for (int m = gw; m < MT; m += NGW) rms_row_to_bf16_g(m < MP ? C.xp + (size_t)m * DM : C.xs + (size_t)(m - MP) * DM, gmix, U + (size_t)m * DM, lane);
.LBB0_32:
	v_lshl_add_u64 v[60:61], v[34:35], 4, s[34:35]
	global_load_dwordx4 v[44:47], v[60:61], off nt
	global_load_dwordx4 v[48:51], v[60:61], off offset:1024 nt
	global_load_dwordx4 v[52:55], v[60:61], off offset:2048 nt
	global_load_dwordx4 v[56:59], v[60:61], off offset:3072 nt
	v_add_co_u32_e32 v60, vcc, s3, v60
	s_lshl_b64 s[10:11], s[30:31], 12
	s_nop 0
	v_addc_co_u32_e32 v61, vcc, 0, v61, vcc
	global_load_dwordx4 v[64:67], v[60:61], off nt
	global_load_dwordx4 v[68:71], v[60:61], off offset:1024 nt
	global_load_dwordx4 v[72:75], v[60:61], off offset:3072 nt
	global_load_dwordx4 v[76:79], v[60:61], off offset:2048 nt
	s_add_u32 s28, s28, s38
	s_addc_u32 s29, s29, s39
	s_add_u32 s24, s24, s26
	s_addc_u32 s25, s25, s27
	s_cmp_gt_i32 s28, 0x81ff
	s_waitcnt vmcnt(7)
	v_mov_b32_e32 v80, v45
	s_waitcnt vmcnt(6)
	v_mov_b32_e32 v81, v49
	v_mov_b32_e32 v84, v47
	v_mov_b32_e32 v85, v51
	v_mov_b32_e32 v60, v44
	v_mov_b32_e32 v61, v48
	v_mov_b32_e32 v82, v46
	v_mov_b32_e32 v83, v50
	s_waitcnt vmcnt(5)
	v_pk_mul_f32 v[86:87], v[54:55], v[54:55]
	v_pk_mul_f32 v[88:89], v[52:53], v[52:53]
	v_pk_mul_f32 v[80:81], v[80:81], v[80:81]
	v_pk_mul_f32 v[84:85], v[84:85], v[84:85]
	v_pk_mov_b32 v[94:95], v[88:89], v[86:87] op_sel:[1,0]
	v_mov_b32_e32 v89, v87
	v_pk_fma_f32 v[60:61], v[60:61], v[60:61], v[80:81]
	v_pk_fma_f32 v[80:81], v[82:83], v[82:83], v[84:85]
	s_waitcnt vmcnt(4)
	v_mul_f32_e32 v90, v57, v57
	v_mul_f32_e32 v92, v59, v59
	v_pk_add_f32 v[82:83], v[94:95], v[88:89]
	v_pk_add_f32 v[60:61], v[60:61], v[80:81]
	s_waitcnt vmcnt(3)
	v_mul_f32_e32 v63, v64, v64
	v_mul_f32_e32 v99, v65, v65
	v_mul_f32_e32 v101, v66, v66
	v_mul_f32_e32 v102, v67, v67
	v_pk_fma_f32 v[90:91], v[56:57], v[56:57], v[90:91] op_sel_hi:[1,1,0]
	v_pk_fma_f32 v[92:93], v[58:59], v[58:59], v[92:93] op_sel_hi:[1,1,0]
	v_pk_add_f32 v[82:83], v[82:83], v[82:83] op_sel:[0,1] op_sel_hi:[1,0]
	v_pk_add_f32 v[60:61], v[60:61], v[60:61] op_sel:[0,1] op_sel_hi:[1,0]
	s_waitcnt vmcnt(2)
	v_pk_mul_f32 v[86:87], v[70:71], v[70:71]
	v_pk_mul_f32 v[96:97], v[68:69], v[68:69]
	v_mov_b32_e32 v91, v101
	v_mov_b32_e32 v93, v102
	v_mov_b32_e32 v83, v99
	v_mov_b32_e32 v61, v63
	v_pk_mov_b32 v[84:85], v[96:97], v[86:87] op_sel:[1,0]
	v_mov_b32_e32 v97, v87
	v_pk_add_f32 v[80:81], v[90:91], v[92:93]
	v_pk_add_f32 v[60:61], v[60:61], v[82:83]
	s_waitcnt vmcnt(0)
	v_mul_f32_e32 v98, v77, v77
	v_mul_f32_e32 v100, v79, v79
	v_pk_add_f32 v[84:85], v[84:85], v[96:97]
	v_pk_add_f32 v[60:61], v[60:61], v[80:81]
	v_mul_f32_e32 v103, v72, v72
	v_mul_f32_e32 v104, v73, v73
	v_mul_f32_e32 v105, v74, v74
	v_mul_f32_e32 v106, v75, v75
	v_pk_fma_f32 v[86:87], v[76:77], v[76:77], v[98:99] op_sel_hi:[1,1,0]
	v_pk_fma_f32 v[88:89], v[78:79], v[78:79], v[100:101] op_sel_hi:[1,1,0]
	v_pk_add_f32 v[84:85], v[84:85], v[84:85] op_sel:[0,1] op_sel_hi:[1,0]
	v_pk_add_f32 v[60:61], v[60:61], v[60:61] op_sel:[0,1] op_sel_hi:[1,0]
	v_mov_b32_e32 v87, v105
	v_mov_b32_e32 v89, v106
	v_mov_b32_e32 v85, v104
	v_mov_b32_e32 v61, v103
	v_pk_add_f32 v[86:87], v[86:87], v[88:89]
	v_pk_add_f32 v[60:61], v[60:61], v[84:85]
	s_nop 0
	v_pk_add_f32 v[60:61], v[60:61], v[86:87]
	s_nop 0
	v_add_f32_e32 v60, v60, v61
	ds_bpermute_b32 v61, v1, v60
	s_waitcnt lgkmcnt(0)
	v_add_f32_e32 v60, v60, v61
	ds_bpermute_b32 v61, v38, v60
	s_waitcnt lgkmcnt(0)
	v_add_f32_e32 v60, v60, v61
	ds_bpermute_b32 v61, v39, v60
	s_waitcnt lgkmcnt(0)
	v_add_f32_e32 v60, v60, v61
	ds_bpermute_b32 v61, v40, v60
	s_waitcnt lgkmcnt(0)
	v_add_f32_e32 v60, v60, v61
	ds_bpermute_b32 v61, v41, v60
	s_waitcnt lgkmcnt(0)
	v_add_f32_e32 v60, v60, v61
	ds_bpermute_b32 v61, v42, v60
	s_waitcnt lgkmcnt(0)
	v_add_f32_e32 v60, v60, v61
	v_fmamk_f32 v60, v60, 0x3a000000, v43
	v_mul_f32_e32 v61, 0x4b800000, v60
	v_cmp_gt_f32_e32 vcc, s8, v60
	s_nop 1
	v_cndmask_b32_e32 v60, v60, v61, vcc
	v_rsq_f32_e32 v63, v60
	v_lshl_add_u64 v[60:61], v[36:37], 0, s[10:11]
	v_mul_f32_e32 v80, 0x45800000, v63
	v_cndmask_b32_e32 v80, v63, v80, vcc
	v_pk_mul_f32 v[44:45], v[44:45], v[80:81] op_sel_hi:[1,0]
	v_pk_mul_f32 v[46:47], v[46:47], v[80:81] op_sel_hi:[1,0]
	v_pk_mul_f32 v[48:49], v[48:49], v[80:81] op_sel_hi:[1,0]
	v_pk_mul_f32 v[50:51], v[50:51], v[80:81] op_sel_hi:[1,0]
	v_pk_mul_f32 v[52:53], v[52:53], v[80:81] op_sel_hi:[1,0]
	v_pk_mul_f32 v[54:55], v[54:55], v[80:81] op_sel_hi:[1,0]
	v_pk_mul_f32 v[56:57], v[56:57], v[80:81] op_sel_hi:[1,0]
	v_pk_mul_f32 v[58:59], v[58:59], v[80:81] op_sel_hi:[1,0]
	v_pk_mul_f32 v[64:65], v[64:65], v[80:81] op_sel_hi:[1,0]
	v_pk_mul_f32 v[66:67], v[66:67], v[80:81] op_sel_hi:[1,0]
	v_pk_mul_f32 v[68:69], v[68:69], v[80:81] op_sel_hi:[1,0]
	v_pk_mul_f32 v[70:71], v[70:71], v[80:81] op_sel_hi:[1,0]
	v_pk_mul_f32 v[76:77], v[76:77], v[80:81] op_sel_hi:[1,0]
	v_pk_mul_f32 v[78:79], v[78:79], v[80:81] op_sel_hi:[1,0]
	v_pk_mul_f32 v[44:45], v[30:31], v[44:45]
	v_pk_mul_f32 v[46:47], v[32:33], v[46:47]
	v_pk_mul_f32 v[48:49], v[26:27], v[48:49]
	v_pk_mul_f32 v[50:51], v[28:29], v[50:51]
	v_pk_mul_f32 v[52:53], v[22:23], v[52:53]
	v_pk_mul_f32 v[54:55], v[24:25], v[54:55]
	v_pk_mul_f32 v[56:57], v[18:19], v[56:57]
	v_pk_mul_f32 v[58:59], v[20:21], v[58:59]
	v_pk_mul_f32 v[64:65], v[14:15], v[64:65]
	v_pk_mul_f32 v[66:67], v[16:17], v[66:67]
	v_pk_mul_f32 v[68:69], v[10:11], v[68:69]
	v_pk_mul_f32 v[70:71], v[12:13], v[70:71]
	v_pk_mul_f32 v[76:77], v[6:7], v[76:77]
	v_pk_mul_f32 v[78:79], v[8:9], v[78:79]
	v_cvt_pk_bf16_f32 v44, v44, v45
	v_cvt_pk_bf16_f32 v45, v46, v47
	v_cvt_pk_bf16_f32 v46, v48, v49
	v_cvt_pk_bf16_f32 v47, v50, v51
	v_pk_mul_f32 v[72:73], v[72:73], v[80:81] op_sel_hi:[1,0]
	v_cvt_pk_bf16_f32 v48, v52, v53
	v_cvt_pk_bf16_f32 v49, v54, v55
	v_cvt_pk_bf16_f32 v50, v56, v57
	v_cvt_pk_bf16_f32 v51, v58, v59
	v_cvt_pk_bf16_f32 v52, v64, v65
	v_cvt_pk_bf16_f32 v53, v66, v67
	v_cvt_pk_bf16_f32 v54, v68, v69
	v_cvt_pk_bf16_f32 v55, v70, v71
	v_cvt_pk_bf16_f32 v56, v76, v77
	v_cvt_pk_bf16_f32 v57, v78, v79
	global_store_dwordx2 v[60:61], v[44:45], off
	global_store_dwordx2 v[60:61], v[46:47], off offset:512
	global_store_dwordx2 v[60:61], v[48:49], off offset:1024
	global_store_dwordx2 v[60:61], v[50:51], off offset:1536
	global_store_dwordx2 v[60:61], v[52:53], off offset:2048
	global_store_dwordx2 v[60:61], v[54:55], off offset:2560
	global_store_dwordx2 v[60:61], v[56:57], off offset:3072
	v_pk_mul_f32 v[46:47], v[74:75], v[80:81] op_sel_hi:[1,0]
	v_pk_mul_f32 v[72:73], v[2:3], v[72:73]
	v_pk_mul_f32 v[46:47], v[4:5], v[46:47]
	v_cvt_pk_bf16_f32 v44, v72, v73
	v_cvt_pk_bf16_f32 v45, v46, v47
	global_store_dwordx2 v[60:61], v[44:45], off offset:3584
	s_cbranch_scc1 .LBB0_35

; DI unsigned cvtpk(float lo, float hi) { f32x2_t v = {lo, hi}; bf16x2_t b = __builtin_convertvector(v, bf16x2_t); return __builtin_bit_cast(unsigned, b); }
; DI void rms_row_to_bf16(const float* xrow, const float* g, bf16_t* orow, int lane) {
;     f32x4 v[8]; float s = 0.f;
; #pragma unroll
;     for (int j = 0; j < 8; ++j) { v[j] = *((const f32x4*)xrow + lane + 64 * j); s += (v[j][0] * v[j][0] + v[j][1] * v[j][1]) + (v[j][2] * v[j][2] + v[j][3] * v[j][3]); }
;     const float rstd = rsqrtf(wave_sum(s) * (1.0f / DM) + EPS);
; #pragma unroll
;     for (int j = 0; j < 8; ++j) { const f32x4 gg = *((const f32x4*)g + lane + 64 * j); u32x2 w; w.x = cvtpk(v[j][0] * rstd * gg[0], v[j][1] * rstd * gg[1]); w.y = cvtpk(v[j][2] * rstd * gg[2], v[j][3] * rstd * gg[3]);
;         *((u32x2*)orow + lane + 64 * j) = w; }
; }
; DI void p0_prologue(const Ctx& C, LAS unsigned char* lds, int wave, bool first) {
;     ...
;         for (int m = gw; m < 1024; m += NGW) rms_row_to_bf16(C.memp + (size_t)m * DM, C.g_mem, (bf16_t*)(C.ws + WS_MEMN) + (size_t)m * DM, lane);
.LBB0_37:
	global_load_dwordx4 v[22:25], v[12:13], off offset:-4096 nt
	global_load_dwordx4 v[26:29], v[12:13], off offset:-3072 nt
	global_load_dwordx4 v[30:33], v[12:13], off offset:-2048 nt
	global_load_dwordx4 v[36:39], v[12:13], off nt
	global_load_dwordx4 v[40:43], v[12:13], off offset:-1024 nt
	global_load_dwordx4 v[44:47], v[12:13], off offset:1024 nt
	global_load_dwordx4 v[48:51], v[12:13], off offset:2048 nt
	global_load_dwordx4 v[52:55], v[12:13], off offset:3072 nt
	global_load_dwordx4 v[56:59], v[2:3], off nt
	s_add_i32 s8, s8, s38
	v_lshl_add_u64 v[12:13], v[12:13], 0, s[0:1]
	s_cmpk_gt_i32 s8, 0x3ff
	s_waitcnt vmcnt(8)
	v_mov_b32_e32 v64, v23
	s_waitcnt vmcnt(7)
	v_mov_b32_e32 v65, v27
	v_mov_b32_e32 v68, v25
	v_mov_b32_e32 v69, v29
	v_mov_b32_e32 v60, v22
	v_mov_b32_e32 v61, v26
	v_mov_b32_e32 v66, v24
	v_mov_b32_e32 v67, v28
	s_waitcnt vmcnt(6)
	v_pk_mul_f32 v[70:71], v[32:33], v[32:33]
	v_pk_mul_f32 v[72:73], v[30:31], v[30:31]
	v_pk_mul_f32 v[64:65], v[64:65], v[64:65]
	v_pk_mul_f32 v[68:69], v[68:69], v[68:69]
	v_pk_mov_b32 v[86:87], v[72:73], v[70:71] op_sel:[1,0]
	v_mov_b32_e32 v73, v71
	v_pk_fma_f32 v[60:61], v[60:61], v[60:61], v[64:65]
	v_pk_fma_f32 v[64:65], v[66:67], v[66:67], v[68:69]
	s_waitcnt vmcnt(4)
	v_mul_f32_e32 v74, v41, v41
	v_mul_f32_e32 v76, v43, v43
	v_pk_add_f32 v[66:67], v[86:87], v[72:73]
	v_pk_add_f32 v[60:61], v[60:61], v[64:65]
	v_mul_f32_e32 v35, v36, v36
	v_mul_f32_e32 v63, v37, v37
	v_mul_f32_e32 v85, v38, v38
	v_mul_f32_e32 v88, v39, v39
	v_pk_fma_f32 v[70:71], v[40:41], v[40:41], v[74:75] op_sel_hi:[1,1,0]
	v_pk_fma_f32 v[74:75], v[42:43], v[42:43], v[76:77] op_sel_hi:[1,1,0]
	v_pk_add_f32 v[64:65], v[66:67], v[66:67] op_sel:[0,1] op_sel_hi:[1,0]
	v_pk_add_f32 v[60:61], v[60:61], v[60:61] op_sel:[0,1] op_sel_hi:[1,0]
	s_waitcnt vmcnt(3)
	v_pk_mul_f32 v[78:79], v[46:47], v[46:47]
	v_pk_mul_f32 v[80:81], v[44:45], v[44:45]
	v_mov_b32_e32 v71, v85
	v_mov_b32_e32 v75, v88
	v_mov_b32_e32 v65, v63
	v_mov_b32_e32 v61, v35
	v_pk_mov_b32 v[76:77], v[80:81], v[78:79] op_sel:[1,0]
	v_mov_b32_e32 v81, v79
	v_pk_add_f32 v[66:67], v[70:71], v[74:75]
	v_pk_add_f32 v[60:61], v[60:61], v[64:65]
	s_waitcnt vmcnt(2)
	v_mul_f32_e32 v82, v49, v49
	v_mul_f32_e32 v84, v51, v51
	v_pk_add_f32 v[68:69], v[76:77], v[80:81]
	v_pk_add_f32 v[60:61], v[60:61], v[66:67]
	s_waitcnt vmcnt(1)
	v_mul_f32_e32 v89, v52, v52
	v_mul_f32_e32 v90, v53, v53
	v_mul_f32_e32 v91, v54, v54
	v_mul_f32_e32 v92, v55, v55
	v_pk_fma_f32 v[78:79], v[48:49], v[48:49], v[82:83] op_sel_hi:[1,1,0]
	v_pk_fma_f32 v[82:83], v[50:51], v[50:51], v[84:85] op_sel_hi:[1,1,0]
	v_pk_add_f32 v[68:69], v[68:69], v[68:69] op_sel:[0,1] op_sel_hi:[1,0]
	v_pk_add_f32 v[60:61], v[60:61], v[60:61] op_sel:[0,1] op_sel_hi:[1,0]
	v_mov_b32_e32 v79, v91
	v_mov_b32_e32 v83, v92
	v_mov_b32_e32 v69, v90
	v_mov_b32_e32 v61, v89
	v_pk_add_f32 v[70:71], v[78:79], v[82:83]
	v_pk_add_f32 v[60:61], v[60:61], v[68:69]
	s_nop 0
	v_pk_add_f32 v[60:61], v[60:61], v[70:71]
	s_nop 0
	v_add_f32_e32 v35, v60, v61
	ds_bpermute_b32 v60, v1, v35
	s_waitcnt lgkmcnt(0)
	v_add_f32_e32 v35, v35, v60
	ds_bpermute_b32 v60, v16, v35
	s_waitcnt lgkmcnt(0)
	v_add_f32_e32 v35, v35, v60
	ds_bpermute_b32 v60, v17, v35
	s_waitcnt lgkmcnt(0)
	v_add_f32_e32 v35, v35, v60
	ds_bpermute_b32 v60, v18, v35
	s_waitcnt lgkmcnt(0)
	v_add_f32_e32 v35, v35, v60
	ds_bpermute_b32 v60, v19, v35
	s_waitcnt lgkmcnt(0)
	v_add_f32_e32 v35, v35, v60
	ds_bpermute_b32 v60, v20, v35
	s_waitcnt lgkmcnt(0)
	v_add_f32_e32 v35, v35, v60
	v_fmamk_f32 v35, v35, 0x3a000000, v21
	v_mul_f32_e32 v60, 0x4b800000, v35
	v_cmp_gt_f32_e32 vcc, s3, v35
	s_nop 1
	v_cndmask_b32_e32 v35, v35, v60, vcc
	v_rsq_f32_e32 v35, v35
	s_nop 0
	v_mul_f32_e32 v60, 0x45800000, v35
	v_cndmask_b32_e32 v60, v35, v60, vcc
	v_pk_mul_f32 v[22:23], v[22:23], v[60:61] op_sel_hi:[1,0]
	v_pk_mul_f32 v[24:25], v[24:25], v[60:61] op_sel_hi:[1,0]
	s_waitcnt vmcnt(0)
	v_pk_mul_f32 v[22:23], v[56:57], v[22:23]
	v_pk_mul_f32 v[24:25], v[58:59], v[24:25]
	v_cvt_pk_bf16_f32 v22, v22, v23
	v_cvt_pk_bf16_f32 v23, v24, v25
	global_store_dwordx2 v[14:15], v[22:23], off
	global_load_dwordx4 v[22:25], v[2:3], off offset:1024 nt
	v_pk_mul_f32 v[26:27], v[26:27], v[60:61] op_sel_hi:[1,0]
	v_pk_mul_f32 v[28:29], v[28:29], v[60:61] op_sel_hi:[1,0]
	s_waitcnt vmcnt(0)
	v_pk_mul_f32 v[22:23], v[22:23], v[26:27]
	v_pk_mul_f32 v[24:25], v[24:25], v[28:29]
	v_cvt_pk_bf16_f32 v22, v22, v23
	v_cvt_pk_bf16_f32 v23, v24, v25
	global_store_dwordx2 v[14:15], v[22:23], off offset:512
	global_load_dwordx4 v[22:25], v[2:3], off offset:2048 nt
	v_pk_mul_f32 v[26:27], v[30:31], v[60:61] op_sel_hi:[1,0]
	v_pk_mul_f32 v[28:29], v[32:33], v[60:61] op_sel_hi:[1,0]
	s_waitcnt vmcnt(0)
	v_pk_mul_f32 v[22:23], v[22:23], v[26:27]
	v_pk_mul_f32 v[24:25], v[24:25], v[28:29]
	v_cvt_pk_bf16_f32 v22, v22, v23
	v_cvt_pk_bf16_f32 v23, v24, v25
	global_store_dwordx2 v[14:15], v[22:23], off offset:1024
	global_load_dwordx4 v[22:25], v[2:3], off offset:3072 nt
	v_pk_mul_f32 v[26:27], v[40:41], v[60:61] op_sel_hi:[1,0]
	v_pk_mul_f32 v[28:29], v[42:43], v[60:61] op_sel_hi:[1,0]
	s_waitcnt vmcnt(0)
	v_pk_mul_f32 v[22:23], v[22:23], v[26:27]
	v_pk_mul_f32 v[24:25], v[24:25], v[28:29]
	v_cvt_pk_bf16_f32 v22, v22, v23
	v_cvt_pk_bf16_f32 v23, v24, v25
	global_store_dwordx2 v[14:15], v[22:23], off offset:1536
	global_load_dwordx4 v[22:25], v[4:5], off nt
	v_pk_mul_f32 v[26:27], v[36:37], v[60:61] op_sel_hi:[1,0]
	v_pk_mul_f32 v[28:29], v[38:39], v[60:61] op_sel_hi:[1,0]
	s_waitcnt vmcnt(0)
	v_pk_mul_f32 v[22:23], v[22:23], v[26:27]
	v_pk_mul_f32 v[24:25], v[24:25], v[28:29]
	v_cvt_pk_bf16_f32 v22, v22, v23
	v_cvt_pk_bf16_f32 v23, v24, v25
	global_store_dwordx2 v[14:15], v[22:23], off offset:2048
	global_load_dwordx4 v[22:25], v[6:7], off nt
	v_pk_mul_f32 v[26:27], v[44:45], v[60:61] op_sel_hi:[1,0]
	v_pk_mul_f32 v[28:29], v[46:47], v[60:61] op_sel_hi:[1,0]
	s_waitcnt vmcnt(0)
	v_pk_mul_f32 v[22:23], v[22:23], v[26:27]
	v_pk_mul_f32 v[24:25], v[24:25], v[28:29]
	v_cvt_pk_bf16_f32 v22, v22, v23
	v_cvt_pk_bf16_f32 v23, v24, v25
	global_store_dwordx2 v[14:15], v[22:23], off offset:2560
	global_load_dwordx4 v[22:25], v[8:9], off nt
	v_pk_mul_f32 v[26:27], v[48:49], v[60:61] op_sel_hi:[1,0]
	v_pk_mul_f32 v[28:29], v[50:51], v[60:61] op_sel_hi:[1,0]
	s_waitcnt vmcnt(0)
	v_pk_mul_f32 v[22:23], v[26:27], v[22:23]
	v_pk_mul_f32 v[24:25], v[28:29], v[24:25]
	v_cvt_pk_bf16_f32 v22, v22, v23
	v_cvt_pk_bf16_f32 v23, v24, v25
	global_store_dwordx2 v[14:15], v[22:23], off offset:3072
	global_load_dwordx4 v[22:25], v[10:11], off nt
	v_pk_mul_f32 v[26:27], v[52:53], v[60:61] op_sel_hi:[1,0]
	v_pk_mul_f32 v[28:29], v[54:55], v[60:61] op_sel_hi:[1,0]
	s_waitcnt vmcnt(0)
	v_pk_mul_f32 v[22:23], v[26:27], v[22:23]
	v_pk_mul_f32 v[24:25], v[28:29], v[24:25]
	v_cvt_pk_bf16_f32 v22, v22, v23
	v_cvt_pk_bf16_f32 v23, v24, v25
	global_store_dwordx2 v[14:15], v[22:23], off offset:3584
	v_lshl_add_u64 v[14:15], v[14:15], 0, s[12:13]
	s_cbranch_scc0 .LBB0_37

; DI void store8bf(bf16_t* p, f32x4 a, f32x4 b) { u32x4 w; w.x = cvtpk(a[0], a[1]); w.y = cvtpk(a[2], a[3]); w.z = cvtpk(b[0], b[1]); w.w = cvtpk(b[2], b[3]); *(u32x4*)p = w; }
; DI void p0_prologue(const Ctx& C, LAS unsigned char* lds, int wave, bool first) {
;     ...
;     for (int i = gt; i < 2 * 8 * 256 * 128; i += NGT) { const int which = i >= 8 * 256 * 128, e = (i - which * 8 * 256 * 128) * 8;
;         const float* src = (which ? C.cmemv : C.cmemk) + e; bf16_t* dst = (bf16_t*)(C.ws + (which ? WS_MV : WS_MK)) + (size_t)1024 * 1024 + e;
;         store8bf(dst, *(const f32x4*)src, *(const f32x4*)(src + 4)); }
.LBB0_40:
	v_cmp_lt_i32_e32 vcc, s3, v11
	s_nop 1
	v_cndmask_b32_e32 v4, 0, v1, vcc
	v_add_lshl_u32 v20, v4, v11, 3
	v_cndmask_b32_e32 v13, v7, v8, vcc
	v_cndmask_b32_e32 v12, v9, v10, vcc
	v_ashrrev_i32_e32 v21, 31, v20
	v_lshl_add_u64 v[16:17], v[20:21], 2, v[12:13]
	global_load_dwordx4 v[12:15], v[16:17], off nt
	s_nop 0
	global_load_dwordx4 v[16:19], v[16:17], off offset:16 nt
	v_cndmask_b32_e32 v4, v3, v6, vcc
	v_add_u32_e32 v11, s68, v11
	v_lshl_add_u64 v[22:23], s[42:43], 0, v[4:5]
	v_cmp_lt_i32_e32 vcc, s8, v11
	v_lshl_add_u64 v[20:21], v[20:21], 1, v[22:23]
	s_or_b64 s[12:13], vcc, s[12:13]
	v_add_co_u32_e32 v20, vcc, 0x200000, v20
	s_waitcnt vmcnt(1)
	v_cvt_pk_bf16_f32 v12, v12, v13
	v_addc_co_u32_e32 v21, vcc, 0, v21, vcc
	v_cvt_pk_bf16_f32 v13, v14, v15
	s_waitcnt vmcnt(0)
	v_cvt_pk_bf16_f32 v14, v16, v17
	v_cvt_pk_bf16_f32 v15, v18, v19
	global_store_dwordx4 v[20:21], v[12:15], off
	s_andn2_b64 exec, exec, s[12:13]
	s_cbranch_execnz .LBB0_40

; DI void p0_prologue(const Ctx& C, LAS unsigned char* lds, int wave, bool first) {
;     ...
;     for (int i = gt; i < 2 * 8 * 64 * 64; i += NGT) { const int which = i >= 8 * 64 * 64, j = i - which * 8 * 64 * 64, b = j >> 12, rem = j & 4095;
;         const float* src = (which ? C.cswav : C.cswak) + ((size_t)b * 128 + 64) * 256 + rem * 4; float* dst = C.out + (which ? O_SWAV_S : O_SWAK_S) + (size_t)b * 128 * 256 + rem * 4;
;         *(f32x4*)dst = *(const f32x4*)src; }
.LBB0_43:
	v_cmp_lt_i32_e64 s[0:1], s8, v12
	v_and_b32_e32 v13, 0x3ffc, v1
	v_mov_b32_e32 v19, v5
	v_cndmask_b32_e64 v4, 0, v3, s[0:1]
	v_add_u32_e32 v4, v4, v12
	v_ashrrev_i32_e32 v16, 12, v4
	v_ashrrev_i32_e32 v17, 31, v16
	v_cndmask_b32_e64 v15, v8, v9, s[0:1]
	v_cndmask_b32_e64 v14, v10, v11, s[0:1]
	v_lshlrev_b64 v[20:21], 17, v[16:17]
	v_lshlrev_b32_e32 v18, 2, v13
	v_lshl_add_u64 v[14:15], v[14:15], 0, v[20:21]
	v_lshl_add_u64 v[14:15], v[14:15], 0, v[18:19]
	v_add_co_u32_e32 v14, vcc, 0x10000, v14
	v_cndmask_b32_e64 v4, v6, v7, s[0:1]
	s_nop 0
	v_addc_co_u32_e32 v15, vcc, 0, v15, vcc
	global_load_dwordx4 v[14:17], v[14:15], off nt
	v_add_u32_e32 v12, s68, v12
	v_lshl_add_u64 v[22:23], s[26:27], 0, v[4:5]
	v_cmp_lt_i32_e32 vcc, s9, v12
	v_lshl_add_u64 v[20:21], v[22:23], 0, v[20:21]
	v_add_u32_e32 v1, s3, v1
	s_or_b64 s[22:23], vcc, s[22:23]
	v_lshl_add_u64 v[18:19], v[20:21], 0, v[18:19]
	s_waitcnt vmcnt(0)
	global_store_dwordx4 v[18:19], v[14:17], off
	s_andn2_b64 exec, exec, s[22:23]
	s_cbranch_execnz .LBB0_43

; DI unsigned cvtpk(float lo, float hi) { f32x2_t v = {lo, hi}; bf16x2_t b = __builtin_convertvector(v, bf16x2_t); return __builtin_bit_cast(unsigned, b); }
; DI void p0_prologue(const Ctx& C, LAS unsigned char* lds, int wave, bool first) {
;     ...
;     for (int i = gt; i < 64 * 128 * 128; i += NGT) { const int bh = i >> 14, e = (i >> 7) & 127, p = i & 127;
;         ((bf16_t*)(C.ws + WS_S0T))[i] = (bf16_t)(cvtpk(C.sret[((size_t)bh * 128 + dorig(p)) * 128 + e], 0.f) & 0xffffu); }
.LBB0_47:
	v_lshrrev_b32_e32 v6, 7, v9
	v_lshlrev_b32_e32 v18, 4, v9
	v_lshlrev_b32_e32 v20, 4, v8
	v_lshrrev_b32_e32 v21, 1, v9
	v_lshrrev_b32_e32 v22, 1, v8
	v_ashrrev_i32_e32 v16, 14, v8
	v_and_b32_e32 v23, 0x7f, v6
	v_and_b32_e32 v6, 64, v18
	v_and_b32_e32 v18, 64, v20
	v_and_b32_e32 v20, 60, v21
	v_and_b32_e32 v21, 60, v22
	v_ashrrev_i32_e32 v14, 14, v9
	v_ashrrev_i32_e32 v17, 31, v16
	v_or_b32_e32 v6, v6, v20
	v_or_b32_e32 v18, v18, v21
	v_lshrrev_b32_e32 v13, 7, v8
	v_ashrrev_i32_e32 v15, 31, v14
	v_lshlrev_b64 v[16:17], 16, v[16:17]
	v_or_b32_e32 v6, v6, v1
	v_or_b32_e32 v20, v18, v4
	v_and_b32_e32 v13, 0x7f, v13
	v_lshlrev_b64 v[14:15], 16, v[14:15]
	v_lshl_add_u64 v[16:17], s[54:55], 0, v[16:17]
	v_lshlrev_b32_e32 v18, 9, v6
	v_lshlrev_b32_e32 v6, 9, v20
	v_mov_b32_e32 v19, v7
	v_lshl_add_u64 v[14:15], s[54:55], 0, v[14:15]
	v_lshl_add_u64 v[16:17], v[16:17], 0, v[6:7]
	v_lshlrev_b32_e32 v6, 2, v13
	v_lshl_add_u64 v[14:15], v[14:15], 0, v[18:19]
	v_lshl_add_u64 v[16:17], v[16:17], 0, v[6:7]
	v_lshlrev_b32_e32 v6, 2, v23
	v_lshl_add_u64 v[14:15], v[14:15], 0, v[6:7]
	global_load_dword v6, v[16:17], off nt
	global_load_dword v13, v[14:15], off nt
	v_add_u32_e32 v12, -2, v12
	v_ashrrev_i32_e32 v17, 31, v8
	v_mov_b32_e32 v16, v8
	v_cmp_eq_u32_e32 vcc, 0, v12
	v_ashrrev_i32_e32 v15, 31, v9
	v_mov_b32_e32 v14, v9
	v_add_u32_e32 v9, s8, v9
	v_add_u32_e32 v8, s3, v8
	v_lshl_add_u64 v[16:17], v[16:17], 1, s[34:35]
	s_or_b64 s[22:23], vcc, s[22:23]
	v_lshl_add_u64 v[14:15], v[14:15], 1, s[34:35]
	s_waitcnt vmcnt(0)
	v_cvt_pk_bf16_f32 v6, v6, v13
	global_store_short v[16:17], v6, off
	global_store_short_d16_hi v[14:15], v6, off
	s_andn2_b64 exec, exec, s[22:23]
	s_cbranch_execnz .LBB0_47
	s_or_b64 exec, exec, s[22:23]
	v_cmp_ne_u32_e32 vcc, v10, v11
	v_mad_u64_u32 v[6:7], s[8:9], v11, s68, v[2:3]
	s_orn2_b64 s[22:23], vcc, exec
	v_readlane_b32 s44, v250, 49
	v_readlane_b32 s45, v250, 50
	v_readlane_b32 s46, v250, 51
	v_readlane_b32 s47, v250, 52
	v_readlane_b32 s52, v250, 57

; DI unsigned cvtpk(float lo, float hi) { f32x2_t v = {lo, hi}; bf16x2_t b = __builtin_convertvector(v, bf16x2_t); return __builtin_bit_cast(unsigned, b); }
; DI void p0_prologue(const Ctx& C, LAS unsigned char* lds, int wave, bool first) {
;     ...
;     for (int i = gt; i < 64 * 128 * 128; i += NGT) { const int bh = i >> 14, e = (i >> 7) & 127, p = i & 127;
;         ((bf16_t*)(C.ws + WS_S0T))[i] = (bf16_t)(cvtpk(C.sret[((size_t)bh * 128 + dorig(p)) * 128 + e], 0.f) & 0xffffu); }
.LBB0_51:
	v_ashrrev_i32_e32 v12, 14, v6
	v_lshrrev_b32_e32 v10, 1, v6
	v_and_b32_e32 v7, 64, v1
	v_ashrrev_i32_e32 v13, 31, v12
	v_and_b32_e32 v10, 60, v10
	v_or3_b32 v7, v7, v10, v4
	v_lshlrev_b64 v[12:13], 16, v[12:13]
	v_lshrrev_b32_e32 v14, 5, v6
	v_lshl_add_u64 v[12:13], s[18:19], 0, v[12:13]
	v_lshlrev_b32_e32 v10, 9, v7
	v_lshl_add_u64 v[12:13], v[12:13], 0, v[10:11]
	v_and_b32_e32 v10, 0x1fc, v14
	v_lshl_add_u64 v[12:13], v[12:13], 0, v[10:11]
	global_load_dword v7, v[12:13], off nt
	v_add_u32_e32 v6, s68, v6
	v_cmp_lt_i32_e32 vcc, s8, v6
	v_add_u32_e32 v1, s3, v1
	s_or_b64 s[22:23], vcc, s[22:23]
	s_waitcnt vmcnt(0)
	v_cvt_pk_bf16_f32 v7, v7, s0
	global_store_short v[8:9], v7, off
	v_lshl_add_u64 v[8:9], v[8:9], 0, s[0:1]
	s_andn2_b64 exec, exec, s[22:23]
	s_cbranch_execnz .LBB0_51
